# v50 + P4a SSQ loads hoisted to chunk-loop top
# baseline (speedup 1.0000x reference)
.LBB0_351:
	global_load_dword v100, v1, s[42:43]
	global_load_dword v101, v1, s[42:43] offset:4
	v_add_u32_e32 v102, s15, v204
	v_lshlrev_b32_e32 v102, 6, v102
	global_load_dwordx4 v[104:107], v102, s[60:61]
	global_load_dwordx4 v[108:111], v102, s[60:61] offset:16
	global_load_dwordx4 v[112:115], v102, s[60:61] offset:32
	global_load_dwordx4 v[116:119], v102, s[60:61] offset:48
	v_add_u32_e32 v10, s15, v171
	v_add_u32_e32 v34, 16, v10
	v_add_u32_e32 v38, 32, v10
	v_ashrrev_i32_e32 v11, 31, v10
	v_ashrrev_i32_e32 v35, 31, v34
	v_ashrrev_i32_e32 v39, 31, v38
	v_lshlrev_b64 v[50:51], 11, v[10:11]
	v_lshlrev_b64 v[54:55], 11, v[34:35]
	v_lshlrev_b64 v[58:59], 11, v[38:39]
	v_lshl_add_u64 v[30:31], v[4:5], 0, v[50:51]
	v_lshl_add_u64 v[34:35], v[4:5], 0, v[54:55]
	v_lshl_add_u64 v[38:39], v[4:5], 0, v[58:59]
	global_load_dwordx4 v[26:29], v[2:3], off
	v_add_u32_e32 v10, 48, v10
	global_load_dwordx4 v[30:33], v[30:31], off
	v_ashrrev_i32_e32 v11, 31, v10
	global_load_dwordx4 v[34:37], v[34:35], off
	v_lshlrev_b64 v[10:11], 11, v[10:11]
	global_load_dwordx4 v[38:41], v[38:39], off
	v_lshl_add_u64 v[42:43], v[4:5], 0, v[10:11]
	global_load_dwordx4 v[42:45], v[42:43], off
	s_nop 0
	global_load_dwordx4 v[46:49], v[2:3], off offset:64
	v_lshl_add_u64 v[66:67], s[36:37], 0, v[50:51]
	v_lshl_add_u64 v[68:69], s[36:37], 0, v[54:55]
	v_lshl_add_u64 v[50:51], v[66:67], 0, v[0:1]
	v_lshl_add_u64 v[54:55], v[68:69], 0, v[0:1]
	v_lshl_add_u64 v[70:71], s[36:37], 0, v[58:59]
	global_load_dwordx4 v[50:53], v[50:51], off
	v_lshl_add_u64 v[58:59], v[70:71], 0, v[0:1]
	global_load_dwordx4 v[54:57], v[54:55], off
	v_lshl_add_u64 v[10:11], s[36:37], 0, v[10:11]
	global_load_dwordx4 v[58:61], v[58:59], off
	v_lshl_add_u64 v[62:63], v[10:11], 0, v[0:1]
	v_lshl_add_u64 v[72:73], v[68:69], 0, v[6:7]
	s_waitcnt vmcnt(7)
	v_mfma_f32_16x16x32_bf16 v[30:33], v[30:33], v[26:29], 0
	s_waitcnt vmcnt(6)
	v_mfma_f32_16x16x32_bf16 v[34:37], v[34:37], v[26:29], 0
	s_waitcnt vmcnt(5)
	v_mfma_f32_16x16x32_bf16 v[38:41], v[38:41], v[26:29], 0
	s_waitcnt vmcnt(4)
	v_mfma_f32_16x16x32_bf16 v[26:29], v[42:45], v[26:29], 0
	global_load_dwordx4 v[42:45], v[62:63], off
	v_lshl_add_u64 v[62:63], v[66:67], 0, v[6:7]
	v_lshl_add_u64 v[66:67], v[66:67], 0, v[8:9]
	s_waitcnt vmcnt(3)
	v_mfma_f32_16x16x32_bf16 v[30:33], v[50:53], v[46:49], v[30:33]
	global_load_dwordx4 v[50:53], v[62:63], off
	s_nop 0
	global_load_dwordx4 v[62:65], v[2:3], off offset:128
	s_waitcnt vmcnt(4)
	v_mfma_f32_16x16x32_bf16 v[34:37], v[54:57], v[46:49], v[34:37]
	global_load_dwordx4 v[54:57], v[72:73], off
	v_lshl_add_u64 v[72:73], v[70:71], 0, v[6:7]
	s_waitcnt vmcnt(4)
	v_mfma_f32_16x16x32_bf16 v[38:41], v[58:61], v[46:49], v[38:41]
	global_load_dwordx4 v[58:61], v[72:73], off
	v_lshl_add_u64 v[72:73], v[10:11], 0, v[6:7]
	v_lshl_add_u64 v[10:11], v[10:11], 0, v[8:9]
	s_waitcnt vmcnt(2)
	v_mfma_f32_16x16x32_bf16 v[30:33], v[50:53], v[62:65], v[30:33]
	v_mfma_f32_16x16x32_bf16 v[26:29], v[42:45], v[46:49], v[26:29]
	global_load_dwordx4 v[42:45], v[72:73], off
	global_load_dwordx4 v[46:49], v[2:3], off offset:192
	global_load_dwordx4 v[50:53], v[66:67], off
	s_waitcnt vmcnt(4)
	v_mfma_f32_16x16x32_bf16 v[34:37], v[54:57], v[62:65], v[34:37]
	s_waitcnt vmcnt(3)
	v_mfma_f32_16x16x32_bf16 v[38:41], v[58:61], v[62:65], v[38:41]
	s_waitcnt vmcnt(2)
	v_mfma_f32_16x16x32_bf16 v[26:29], v[42:45], v[62:65], v[26:29]
	global_load_dwordx4 v[42:45], v[10:11], off
	v_lshl_add_u64 v[66:67], v[68:69], 0, v[8:9]
	global_load_dwordx4 v[54:57], v[66:67], off
	v_lshl_add_u64 v[66:67], v[70:71], 0, v[8:9]
	global_load_dwordx4 v[58:61], v[66:67], off
	v_add_u32_e32 v10, s15, v204
	v_ashrrev_i32_e32 v11, 31, v10
	s_waitcnt vmcnt(3)
	v_mfma_f32_16x16x32_bf16 v[30:33], v[50:53], v[46:49], v[30:33]
	v_lshlrev_b64 v[50:51], 6, v[10:11]
	v_lshl_add_u64 v[66:67], s[60:61], 0, v[50:51]
	v_mov_b32_e32 v50, v104
	v_mov_b32_e32 v51, v105
	v_mov_b32_e32 v52, v106
	v_mov_b32_e32 v53, v107
	v_lshl_add_u64 v[10:11], v[10:11], 2, s[38:39]
	s_waitcnt vmcnt(2)
	v_mfma_f32_16x16x32_bf16 v[26:29], v[42:45], v[46:49], v[26:29]
	s_waitcnt vmcnt(0)
	v_add_f32_e32 v25, v50, v51
	v_mfma_f32_16x16x32_bf16 v[34:37], v[54:57], v[46:49], v[34:37]
	v_mov_b32_e32 v54, v108
	v_mov_b32_e32 v55, v109
	v_mov_b32_e32 v56, v110
	v_mov_b32_e32 v57, v111
	v_mov_b32_e32 v62, v112
	v_mov_b32_e32 v63, v113
	v_mov_b32_e32 v64, v114
	v_mov_b32_e32 v65, v115
	v_mfma_f32_16x16x32_bf16 v[38:41], v[58:61], v[46:49], v[38:41]
	v_mov_b32_e32 v58, v116
	v_mov_b32_e32 v59, v117
	v_mov_b32_e32 v60, v118
	v_mov_b32_e32 v61, v119
	ds_write2_b32 v19, v30, v31 offset1:16
	ds_write2_b32 v19, v32, v33 offset0:32 offset1:48
	s_nop 1
	ds_write2_b32 v22, v34, v35 offset1:16
	ds_write2_b32 v22, v36, v37 offset0:32 offset1:48
	s_nop 0
	ds_write2_b32 v23, v38, v39 offset1:16
	ds_write2_b32 v23, v40, v41 offset0:32 offset1:48
	ds_write2_b32 v24, v26, v27 offset1:16
	ds_write2_b32 v24, v28, v29 offset0:32 offset1:48
	s_waitcnt lgkmcnt(0)
	s_barrier
	v_mov_b32_e32 v34, v100
	v_add_f32_e32 v26, v52, v53
	v_add_f32_e32 v25, v25, v26
	s_waitcnt vmcnt(2)
	v_add_f32_e32 v27, v54, v55
	v_add_f32_e32 v28, v56, v57
	s_waitcnt vmcnt(1)
	v_add_f32_e32 v29, v62, v63
	v_add_f32_e32 v30, v64, v65
	v_add_f32_e32 v26, v27, v28
	s_waitcnt vmcnt(0)
	v_add_f32_e32 v31, v58, v59
	v_add_f32_e32 v32, v60, v61
	v_add_f32_e32 v27, v29, v30
	v_add_f32_e32 v25, v25, v26
	v_add_f32_e32 v28, v31, v32
	v_add_f32_e32 v25, v25, v27
	v_add_f32_e32 v25, v25, v28
	v_fmamk_f32 v25, v25, 0x3a800000, v20
	v_mul_f32_e32 v26, 0x4f800000, v25
	v_cmp_gt_f32_e32 vcc, s57, v25
	s_nop 1
	v_cndmask_b32_e32 v25, v25, v26, vcc
	v_sqrt_f32_e32 v26, v25
	s_nop 0
	v_add_u32_e32 v27, -1, v26
	v_add_u32_e32 v28, 1, v26
	v_fma_f32 v29, -v27, v26, v25
	v_fma_f32 v30, -v28, v26, v25
	v_cmp_ge_f32_e64 s[22:23], 0, v29
	s_nop 1
	v_cndmask_b32_e64 v26, v26, v27, s[22:23]
	v_cmp_lt_f32_e64 s[22:23], 0, v30
	s_nop 1
	v_cndmask_b32_e64 v26, v26, v28, s[22:23]
	v_mul_f32_e32 v27, 0x37800000, v26
	v_cndmask_b32_e32 v26, v26, v27, vcc
	v_cmp_class_f32_e32 vcc, v25, v21
	s_nop 1
	v_cndmask_b32_e32 v25, v26, v25, vcc
	v_div_scale_f32 v35, s[22:23], v25, v25, 1.0
	v_rcp_f32_e32 v37, v35
	ds_read2st64_b32 v[26:27], v12 offset1:16
	ds_read2st64_b32 v[28:29], v12 offset0:32 offset1:48
	ds_read2st64_b32 v[30:31], v12 offset0:64 offset1:80
	ds_read2st64_b32 v[32:33], v12 offset0:96 offset1:112
	v_div_scale_f32 v36, vcc, 1.0, v25, 1.0
	v_fma_f32 v38, -v35, v37, 1.0
	s_waitcnt lgkmcnt(3)
	v_add_f32_e32 v26, 0, v26
	v_fmac_f32_e32 v37, v38, v37
	v_add_f32_e32 v26, v26, v27
	v_mul_f32_e32 v38, v36, v37
	s_waitcnt lgkmcnt(2)
	v_add_f32_e32 v26, v26, v28
	v_fma_f32 v39, -v35, v38, v36
	v_add_f32_e32 v26, v26, v29
	v_fmac_f32_e32 v38, v39, v37
	s_waitcnt lgkmcnt(1)
	v_add_f32_e32 v26, v26, v30
	v_fma_f32 v27, -v35, v38, v36
	v_add_f32_e32 v26, v26, v31
	v_div_fmas_f32 v27, v27, v37, v38
	s_waitcnt lgkmcnt(0)
	v_add_f32_e32 v26, v26, v32
	v_div_fixup_f32 v25, v27, v25, 1.0
	v_add_f32_e32 v26, v26, v33
	s_waitcnt vmcnt(0)
	v_fmac_f32_e32 v34, v25, v26
	v_mul_f32_e64 v26, |v34|, s64
	v_exp_f32_e32 v26, v26
	v_min_f32_e32 v27, 0, v34
	v_lshl_add_u64 v[28:29], v[10:11], 0, s[46:47]
	v_add_f32_e32 v26, 1.0, v26
	v_log_f32_e32 v26, v26
	s_nop 0
	v_fmac_f32_e32 v27, 0xbf317218, v26
	ds_bpermute_b32 v26, v13, v27
	s_waitcnt lgkmcnt(0)
	v_add_f32_e32 v26, v27, v26
	v_cndmask_b32_e64 v26, v26, v27, s[8:9]
	ds_bpermute_b32 v27, v14, v26
	s_waitcnt lgkmcnt(0)
	v_add_f32_e32 v27, v26, v27
	v_cndmask_b32_e64 v26, v27, v26, s[10:11]
	ds_bpermute_b32 v27, v15, v26
	s_waitcnt lgkmcnt(0)
	v_add_f32_e32 v27, v26, v27
	v_cndmask_b32_e64 v26, v27, v26, s[12:13]
	ds_bpermute_b32 v27, v16, v26
	s_waitcnt lgkmcnt(0)
	v_add_f32_e32 v27, v26, v27
	v_cndmask_b32_e64 v26, v27, v26, s[16:17]
	ds_bpermute_b32 v27, v17, v26
	s_waitcnt lgkmcnt(0)
	v_add_f32_e32 v27, v26, v27
	v_cndmask_b32_e64 v27, v27, v26, s[18:19]
	ds_bpermute_b32 v26, v18, v27
	s_waitcnt lgkmcnt(0)
	v_add_f32_e32 v26, v27, v26
	v_cndmask_b32_e64 v27, v26, v27, s[20:21]
	global_store_dword v[28:29], v27, off sc1
	s_and_saveexec_b64 s[22:23], s[0:1]
	s_cbranch_execz .LBB0_353
	s_add_i32 s44, s14, s65
	s_ashr_i32 s45, s44, 31
	s_lshl_b64 s[44:45], s[44:45], 2
	s_add_u32 s44, s74, s44
	s_addc_u32 s45, s75, s45
	global_store_dword v1, v26, s[44:45] sc1

.LBB0_443:
	global_load_dword v100, v1, s[40:41]
	global_load_dword v101, v1, s[40:41] offset:4
	v_add_u32_e32 v102, s15, v204
	v_lshlrev_b32_e32 v102, 6, v102
	global_load_dwordx4 v[104:107], v102, s[60:61]
	global_load_dwordx4 v[108:111], v102, s[60:61] offset:16
	global_load_dwordx4 v[112:115], v102, s[60:61] offset:32
	global_load_dwordx4 v[116:119], v102, s[60:61] offset:48
	v_add_u32_e32 v10, s15, v171
	v_add_u32_e32 v34, 16, v10
	v_add_u32_e32 v38, 32, v10
	v_ashrrev_i32_e32 v11, 31, v10
	v_ashrrev_i32_e32 v35, 31, v34
	v_ashrrev_i32_e32 v39, 31, v38
	v_lshlrev_b64 v[50:51], 11, v[10:11]
	v_lshlrev_b64 v[54:55], 11, v[34:35]
	v_lshlrev_b64 v[58:59], 11, v[38:39]
	v_lshl_add_u64 v[30:31], v[4:5], 0, v[50:51]
	v_lshl_add_u64 v[34:35], v[4:5], 0, v[54:55]
	v_lshl_add_u64 v[38:39], v[4:5], 0, v[58:59]
	global_load_dwordx4 v[26:29], v[2:3], off
	v_add_u32_e32 v10, 48, v10
	global_load_dwordx4 v[30:33], v[30:31], off
	v_ashrrev_i32_e32 v11, 31, v10
	global_load_dwordx4 v[34:37], v[34:35], off
	v_lshlrev_b64 v[10:11], 11, v[10:11]
	global_load_dwordx4 v[38:41], v[38:39], off
	v_lshl_add_u64 v[42:43], v[4:5], 0, v[10:11]
	global_load_dwordx4 v[42:45], v[42:43], off
	s_nop 0
	global_load_dwordx4 v[46:49], v[2:3], off offset:64
	v_lshl_add_u64 v[66:67], s[36:37], 0, v[50:51]
	v_lshl_add_u64 v[68:69], s[36:37], 0, v[54:55]
	v_lshl_add_u64 v[50:51], v[66:67], 0, v[0:1]
	v_lshl_add_u64 v[54:55], v[68:69], 0, v[0:1]
	v_lshl_add_u64 v[70:71], s[36:37], 0, v[58:59]
	global_load_dwordx4 v[50:53], v[50:51], off
	v_lshl_add_u64 v[58:59], v[70:71], 0, v[0:1]
	global_load_dwordx4 v[54:57], v[54:55], off
	v_lshl_add_u64 v[10:11], s[36:37], 0, v[10:11]
	global_load_dwordx4 v[58:61], v[58:59], off
	v_lshl_add_u64 v[62:63], v[10:11], 0, v[0:1]
	v_lshl_add_u64 v[72:73], v[68:69], 0, v[6:7]
	s_waitcnt vmcnt(7)
	v_mfma_f32_16x16x32_bf16 v[30:33], v[30:33], v[26:29], 0
	s_waitcnt vmcnt(6)
	v_mfma_f32_16x16x32_bf16 v[34:37], v[34:37], v[26:29], 0
	s_waitcnt vmcnt(5)
	v_mfma_f32_16x16x32_bf16 v[38:41], v[38:41], v[26:29], 0
	s_waitcnt vmcnt(4)
	v_mfma_f32_16x16x32_bf16 v[26:29], v[42:45], v[26:29], 0
	global_load_dwordx4 v[42:45], v[62:63], off
	v_lshl_add_u64 v[62:63], v[66:67], 0, v[6:7]
	v_lshl_add_u64 v[66:67], v[66:67], 0, v[8:9]
	s_waitcnt vmcnt(3)
	v_mfma_f32_16x16x32_bf16 v[30:33], v[50:53], v[46:49], v[30:33]
	global_load_dwordx4 v[50:53], v[62:63], off
	s_nop 0
	global_load_dwordx4 v[62:65], v[2:3], off offset:128
	s_waitcnt vmcnt(4)
	v_mfma_f32_16x16x32_bf16 v[34:37], v[54:57], v[46:49], v[34:37]
	global_load_dwordx4 v[54:57], v[72:73], off
	v_lshl_add_u64 v[72:73], v[70:71], 0, v[6:7]
	s_waitcnt vmcnt(4)
	v_mfma_f32_16x16x32_bf16 v[38:41], v[58:61], v[46:49], v[38:41]
	global_load_dwordx4 v[58:61], v[72:73], off
	v_lshl_add_u64 v[72:73], v[10:11], 0, v[6:7]
	v_lshl_add_u64 v[10:11], v[10:11], 0, v[8:9]
	s_waitcnt vmcnt(2)
	v_mfma_f32_16x16x32_bf16 v[30:33], v[50:53], v[62:65], v[30:33]
	v_mfma_f32_16x16x32_bf16 v[26:29], v[42:45], v[46:49], v[26:29]
	global_load_dwordx4 v[42:45], v[72:73], off
	global_load_dwordx4 v[46:49], v[2:3], off offset:192
	global_load_dwordx4 v[50:53], v[66:67], off
	s_waitcnt vmcnt(4)
	v_mfma_f32_16x16x32_bf16 v[34:37], v[54:57], v[62:65], v[34:37]
	s_waitcnt vmcnt(3)
	v_mfma_f32_16x16x32_bf16 v[38:41], v[58:61], v[62:65], v[38:41]
	s_waitcnt vmcnt(2)
	v_mfma_f32_16x16x32_bf16 v[26:29], v[42:45], v[62:65], v[26:29]
	global_load_dwordx4 v[42:45], v[10:11], off
	v_lshl_add_u64 v[66:67], v[68:69], 0, v[8:9]
	global_load_dwordx4 v[54:57], v[66:67], off
	v_lshl_add_u64 v[66:67], v[70:71], 0, v[8:9]
	global_load_dwordx4 v[58:61], v[66:67], off
	v_add_u32_e32 v10, s15, v204
	v_ashrrev_i32_e32 v11, 31, v10
	s_waitcnt vmcnt(3)
	v_mfma_f32_16x16x32_bf16 v[30:33], v[50:53], v[46:49], v[30:33]
	v_lshlrev_b64 v[50:51], 6, v[10:11]
	v_lshl_add_u64 v[66:67], s[60:61], 0, v[50:51]
	v_mov_b32_e32 v50, v104
	v_mov_b32_e32 v51, v105
	v_mov_b32_e32 v52, v106
	v_mov_b32_e32 v53, v107
	v_lshl_add_u64 v[10:11], v[10:11], 2, s[38:39]
	s_waitcnt vmcnt(2)
	v_mfma_f32_16x16x32_bf16 v[26:29], v[42:45], v[46:49], v[26:29]
	s_waitcnt vmcnt(0)
	v_add_f32_e32 v25, v50, v51
	v_mfma_f32_16x16x32_bf16 v[34:37], v[54:57], v[46:49], v[34:37]
	v_mov_b32_e32 v54, v108
	v_mov_b32_e32 v55, v109
	v_mov_b32_e32 v56, v110
	v_mov_b32_e32 v57, v111
	v_mov_b32_e32 v62, v112
	v_mov_b32_e32 v63, v113
	v_mov_b32_e32 v64, v114
	v_mov_b32_e32 v65, v115
	v_mfma_f32_16x16x32_bf16 v[38:41], v[58:61], v[46:49], v[38:41]
	v_mov_b32_e32 v58, v116
	v_mov_b32_e32 v59, v117
	v_mov_b32_e32 v60, v118
	v_mov_b32_e32 v61, v119
	ds_write2_b32 v19, v30, v31 offset1:16
	ds_write2_b32 v19, v32, v33 offset0:32 offset1:48
	s_nop 1
	ds_write2_b32 v22, v34, v35 offset1:16
	ds_write2_b32 v22, v36, v37 offset0:32 offset1:48
	s_nop 0
	ds_write2_b32 v23, v38, v39 offset1:16
	ds_write2_b32 v23, v40, v41 offset0:32 offset1:48
	ds_write2_b32 v24, v26, v27 offset1:16
	ds_write2_b32 v24, v28, v29 offset0:32 offset1:48
	s_waitcnt lgkmcnt(0)
	s_barrier
	v_mov_b32_e32 v34, v100
	v_add_f32_e32 v26, v52, v53
	v_add_f32_e32 v25, v25, v26
	s_waitcnt vmcnt(2)
	v_add_f32_e32 v27, v54, v55
	v_add_f32_e32 v28, v56, v57
	s_waitcnt vmcnt(1)
	v_add_f32_e32 v29, v62, v63
	v_add_f32_e32 v30, v64, v65
	v_add_f32_e32 v26, v27, v28
	s_waitcnt vmcnt(0)
	v_add_f32_e32 v31, v58, v59
	v_add_f32_e32 v32, v60, v61
	v_add_f32_e32 v27, v29, v30
	v_add_f32_e32 v25, v25, v26
	v_add_f32_e32 v28, v31, v32
	v_add_f32_e32 v25, v25, v27
	v_add_f32_e32 v25, v25, v28
	v_fmamk_f32 v25, v25, 0x3a800000, v20
	v_mul_f32_e32 v26, 0x4f800000, v25
	v_cmp_gt_f32_e32 vcc, s57, v25
	s_nop 1
	v_cndmask_b32_e32 v25, v25, v26, vcc
	v_sqrt_f32_e32 v26, v25
	s_nop 0
	v_add_u32_e32 v27, -1, v26
	v_add_u32_e32 v28, 1, v26
	v_fma_f32 v29, -v27, v26, v25
	v_fma_f32 v30, -v28, v26, v25
	v_cmp_ge_f32_e64 s[22:23], 0, v29
	s_nop 1
	v_cndmask_b32_e64 v26, v26, v27, s[22:23]
	v_cmp_lt_f32_e64 s[22:23], 0, v30
	s_nop 1
	v_cndmask_b32_e64 v26, v26, v28, s[22:23]
	v_mul_f32_e32 v27, 0x37800000, v26
	v_cndmask_b32_e32 v26, v26, v27, vcc
	v_cmp_class_f32_e32 vcc, v25, v21
	s_nop 1
	v_cndmask_b32_e32 v25, v26, v25, vcc
	v_div_scale_f32 v35, s[22:23], v25, v25, 1.0
	v_rcp_f32_e32 v37, v35
	ds_read2st64_b32 v[26:27], v12 offset1:16
	ds_read2st64_b32 v[28:29], v12 offset0:32 offset1:48
	ds_read2st64_b32 v[30:31], v12 offset0:64 offset1:80
	ds_read2st64_b32 v[32:33], v12 offset0:96 offset1:112
	v_div_scale_f32 v36, vcc, 1.0, v25, 1.0
	v_fma_f32 v38, -v35, v37, 1.0
	s_waitcnt lgkmcnt(3)
	v_add_f32_e32 v26, 0, v26
	v_fmac_f32_e32 v37, v38, v37
	v_add_f32_e32 v26, v26, v27
	v_mul_f32_e32 v38, v36, v37
	s_waitcnt lgkmcnt(2)
	v_add_f32_e32 v26, v26, v28
	v_fma_f32 v39, -v35, v38, v36
	v_add_f32_e32 v26, v26, v29
	v_fmac_f32_e32 v38, v39, v37
	s_waitcnt lgkmcnt(1)
	v_add_f32_e32 v26, v26, v30
	v_fma_f32 v27, -v35, v38, v36
	v_add_f32_e32 v26, v26, v31
	v_div_fmas_f32 v27, v27, v37, v38
	s_waitcnt lgkmcnt(0)
	v_add_f32_e32 v26, v26, v32
	v_div_fixup_f32 v25, v27, v25, 1.0
	v_add_f32_e32 v26, v26, v33
	s_waitcnt vmcnt(0)
	v_fmac_f32_e32 v34, v25, v26
	v_mul_f32_e64 v26, |v34|, s64
	v_exp_f32_e32 v26, v26
	v_min_f32_e32 v27, 0, v34
	v_lshl_add_u64 v[28:29], v[10:11], 0, s[58:59]
	v_add_f32_e32 v26, 1.0, v26
	v_log_f32_e32 v26, v26
	s_nop 0
	v_fmac_f32_e32 v27, 0xbf317218, v26
	ds_bpermute_b32 v26, v13, v27
	s_waitcnt lgkmcnt(0)
	v_add_f32_e32 v26, v27, v26
	v_cndmask_b32_e64 v26, v26, v27, s[8:9]
	ds_bpermute_b32 v27, v14, v26
	s_waitcnt lgkmcnt(0)
	v_add_f32_e32 v27, v26, v27
	v_cndmask_b32_e64 v26, v27, v26, s[10:11]
	ds_bpermute_b32 v27, v15, v26
	s_waitcnt lgkmcnt(0)
	v_add_f32_e32 v27, v26, v27
	v_cndmask_b32_e64 v26, v27, v26, s[12:13]
	ds_bpermute_b32 v27, v16, v26
	s_waitcnt lgkmcnt(0)
	v_add_f32_e32 v27, v26, v27
	v_cndmask_b32_e64 v26, v27, v26, s[16:17]
	ds_bpermute_b32 v27, v17, v26
	s_waitcnt lgkmcnt(0)
	v_add_f32_e32 v27, v26, v27
	v_cndmask_b32_e64 v27, v27, v26, s[18:19]
	ds_bpermute_b32 v26, v18, v27
	s_waitcnt lgkmcnt(0)
	v_add_f32_e32 v26, v27, v26
	v_cndmask_b32_e64 v27, v26, v27, s[20:21]
	global_store_dword v[28:29], v27, off sc1
	s_and_saveexec_b64 s[22:23], s[0:1]
	s_cbranch_execz .LBB0_445
	s_add_i32 s66, s14, s65
	s_ashr_i32 s67, s66, 31
	s_lshl_b64 s[66:67], s[66:67], 2
	s_add_u32 s66, s74, s66
	s_addc_u32 s67, s75, s67
	global_store_dword v1, v26, s[66:67] sc1
